# EpiDilVT: the 16 serialized per-column rstd loads of each V-transpose tile issued as two batches of 8 (one wait each)
# speedup vs baseline: 1.0027x; 1.0027x over previous
.LBB0_530:
	s_lshl_b32 s9, s8, 8
	s_cmp_lt_i32 s8, 64
	s_cselect_b32 s4, s11, 0x4000
	s_cmp_gt_i32 s8, 31
	s_mul_hi_u32 s8, s4, s94
	s_mul_i32 s33, s8, s93
	s_cselect_b32 s5, s4, 0
	s_sub_i32 s4, s4, s33
	s_add_i32 s33, s8, 1
	s_sub_i32 s37, s4, s93
	s_cmp_ge_u32 s4, s93
	s_cselect_b32 s8, s33, s8
	s_cselect_b32 s4, s37, s4
	s_add_i32 s33, s8, 1
	s_cmp_ge_u32 s4, s93
	s_cselect_b32 s4, s33, s8
	s_xor_b32 s4, s4, s92
	s_sub_i32 s4, s4, s92
	s_abs_i32 s46, s4
	v_cvt_f32_u32_e32 v128, s46
	s_sub_i32 s47, 0, s46
	s_sub_i32 s8, s9, s5
	s_abs_i32 s37, s8
	v_rcp_iflag_f32_e32 v128, v128
	s_xor_b32 s33, s8, s4
	s_ashr_i32 s33, s33, 31
	v_mov_b32_e32 v152, v179
	v_mul_f32_e32 v128, 0x4f7ffffe, v128
	v_cvt_u32_f32_e32 v128, v128
	s_nop 0
	v_readfirstlane_b32 s36, v152
	v_readfirstlane_b32 s48, v128
	s_mul_i32 s47, s47, s48
	s_mul_hi_u32 s47, s48, s47
	s_add_i32 s48, s48, s47
	s_mul_hi_u32 s47, s37, s48
	s_mul_i32 s48, s47, s46
	s_sub_i32 s37, s37, s48
	s_add_i32 s48, s47, 1
	s_sub_i32 s49, s37, s46
	s_cmp_ge_u32 s37, s46
	s_cselect_b32 s47, s48, s47
	s_cselect_b32 s37, s49, s37
	s_add_i32 s48, s47, 1
	s_cmp_ge_u32 s37, s46
	s_cselect_b32 s37, s48, s47
	s_xor_b32 s37, s37, s33
	s_sub_i32 s33, s37, s33
	s_mul_i32 s4, s33, s4
	s_sub_i32 s4, s8, s4
	s_mul_i32 s4, s4, s61
	s_add_i32 s8, s33, s5
	s_add_i32 s8, s8, s4
	s_lshr_b32 s4, s36, 1
	v_lshrrev_b32_e32 v128, 1, v152
	s_and_b32 s33, s4, 0x60
	v_and_b32_e32 v151, 24, v128
	v_or_b32_e32 v128, s33, v151
	v_mul_lo_u32 v128, v128, s61
	v_add_u32_e32 v144, s8, v128
	v_ashrrev_i32_e32 v145, 31, v144
	v_lshl_add_u64 v[128:129], v[144:145], 4, s[24:25]
	v_mov_b32_e32 v164, v144
	v_ashrrev_i32_e32 v165, 31, v164
	v_lshl_add_u64 v[162:163], v[164:165], 4, s[24:25]
	global_load_dwordx4 v[184:187], v[162:163], off
	v_add_u32_e32 v164, s61, v164
	v_ashrrev_i32_e32 v165, 31, v164
	v_lshl_add_u64 v[162:163], v[164:165], 4, s[24:25]
	global_load_dwordx4 v[188:191], v[162:163], off
	v_add_u32_e32 v164, s61, v164
	v_ashrrev_i32_e32 v165, 31, v164
	v_lshl_add_u64 v[162:163], v[164:165], 4, s[24:25]
	global_load_dwordx4 v[192:195], v[162:163], off
	v_add_u32_e32 v164, s61, v164
	v_ashrrev_i32_e32 v165, 31, v164
	v_lshl_add_u64 v[162:163], v[164:165], 4, s[24:25]
	global_load_dwordx4 v[196:199], v[162:163], off
	v_add_u32_e32 v164, s61, v164
	v_ashrrev_i32_e32 v165, 31, v164
	v_lshl_add_u64 v[162:163], v[164:165], 4, s[24:25]
	global_load_dwordx4 v[214:217], v[162:163], off
	v_add_u32_e32 v164, s61, v164
	v_ashrrev_i32_e32 v165, 31, v164
	v_lshl_add_u64 v[162:163], v[164:165], 4, s[24:25]
	global_load_dwordx4 v[218:221], v[162:163], off
	v_add_u32_e32 v164, s61, v164
	v_ashrrev_i32_e32 v165, 31, v164
	v_lshl_add_u64 v[162:163], v[164:165], 4, s[24:25]
	global_load_dwordx4 v[222:225], v[162:163], off
	v_add_u32_e32 v164, s61, v164
	v_ashrrev_i32_e32 v165, 31, v164
	v_lshl_add_u64 v[162:163], v[164:165], 4, s[24:25]
	global_load_dwordx4 v[226:229], v[162:163], off
	s_waitcnt vmcnt(0)
	v_add_u32_e32 v156, s61, v144
	v_ashrrev_i32_e32 v157, 31, v156
	s_mov_b32 s4, 0x358637bd
	s_mov_b32 s46, 0x3a800000
	v_lshlrev_b32_e32 v176, 1, v151
	v_mov_b32_e32 v128, v184
	v_mov_b32_e32 v129, v185
	v_mov_b32_e32 v130, v186
	v_mov_b32_e32 v131, v187
	v_mov_b32_e32 v146, v129
	v_mov_b32_e32 v147, v130
	v_mov_b32_e32 v129, v131
	v_pk_add_f32 v[146:147], v[146:147], v[128:129]
	v_lshl_add_u64 v[128:129], v[156:157], 4, s[24:25]
	v_mov_b32_e32 v128, v188
	v_mov_b32_e32 v129, v189
	v_mov_b32_e32 v130, v190
	v_mov_b32_e32 v131, v191
	v_mov_b32_e32 v144, v129
	v_mov_b32_e32 v145, v130
	v_mov_b32_e32 v129, v131
	v_pk_add_f32 v[128:129], v[144:145], v[128:129]
	v_mov_b32_e32 v131, v146
	v_mov_b32_e32 v130, v128
	v_mov_b32_e32 v146, v129
	v_pk_add_f32 v[128:129], v[130:131], v[146:147]
	v_mov_b64_e32 v[144:145], s[4:5]
	v_pk_fma_f32 v[128:129], v[128:129], s[46:47], v[144:145] op_sel_hi:[1,0,0]
	v_add_u32_e32 v146, s61, v156
	v_mul_f32_e32 v130, 0x4b800000, v129
	v_cmp_gt_f32_e64 s[4:5], s10, v129
	v_cmp_gt_f32_e32 vcc, s10, v128
	v_ashrrev_i32_e32 v147, 31, v146
	v_cndmask_b32_e64 v129, v129, v130, s[4:5]
	v_rsq_f32_e32 v129, v129
	s_nop 0
	v_mul_f32_e32 v130, 0x45800000, v129
	v_cndmask_b32_e64 v153, v129, v130, s[4:5]
	v_mul_f32_e32 v129, 0x4b800000, v128
	v_cndmask_b32_e32 v128, v128, v129, vcc
	v_rsq_f32_e32 v128, v128
	v_mul_f32_e32 v124, v124, v153
	v_mul_f32_e32 v116, v116, v153
	v_mul_f32_e32 v108, v108, v153
	v_mul_f32_e32 v129, 0x45800000, v128
	v_cndmask_b32_e32 v154, v128, v129, vcc
	v_lshl_add_u64 v[128:129], v[146:147], 4, s[24:25]
	v_add_u32_e32 v146, s61, v146
	v_ashrrev_i32_e32 v147, 31, v146
	v_mul_f32_e32 v125, v125, v154
	v_mul_f32_e32 v117, v117, v154
	v_mul_f32_e32 v109, v109, v154
	v_mul_f32_e32 v100, v100, v153
	v_mul_f32_e32 v101, v101, v154
	v_mul_f32_e32 v92, v92, v153
	v_mul_f32_e32 v93, v93, v154
	v_mul_f32_e32 v84, v84, v153
	v_mul_f32_e32 v85, v85, v154
	v_mul_f32_e32 v76, v76, v153
	v_mul_f32_e32 v77, v77, v154
	v_mul_f32_e32 v68, v68, v153
	v_mul_f32_e32 v69, v69, v154
	v_mov_b32_e32 v128, v192
	v_mov_b32_e32 v129, v193
	v_mov_b32_e32 v130, v194
	v_mov_b32_e32 v131, v195
	v_mov_b32_e32 v156, v129
	v_mov_b32_e32 v157, v130
	v_mov_b32_e32 v129, v131
	v_pk_add_f32 v[156:157], v[156:157], v[128:129]
	v_lshl_add_u64 v[128:129], v[146:147], 4, s[24:25]
	v_add_u32_e32 v146, s61, v146
	v_ashrrev_i32_e32 v147, 31, v146
	v_mov_b32_e32 v128, v196
	v_mov_b32_e32 v129, v197
	v_mov_b32_e32 v130, v198
	v_mov_b32_e32 v131, v199
	v_mov_b32_e32 v158, v129
	v_mov_b32_e32 v159, v130
	v_mov_b32_e32 v129, v131
	v_pk_add_f32 v[128:129], v[158:159], v[128:129]
	v_mov_b32_e32 v131, v156
	v_mov_b32_e32 v130, v128
	v_mov_b32_e32 v156, v129
	v_pk_add_f32 v[128:129], v[130:131], v[156:157]
	s_nop 0
	v_pk_fma_f32 v[128:129], v[128:129], s[46:47], v[144:145] op_sel_hi:[1,0,0]
	s_nop 0
	v_mul_f32_e32 v130, 0x4b800000, v129
	v_cmp_gt_f32_e64 s[4:5], s10, v129
	v_cmp_gt_f32_e32 vcc, s10, v128
	s_nop 0
	v_cndmask_b32_e64 v129, v129, v130, s[4:5]
	v_rsq_f32_e32 v129, v129
	s_nop 0
	v_mul_f32_e32 v130, 0x45800000, v129
	v_cndmask_b32_e64 v155, v129, v130, s[4:5]
	v_mul_f32_e32 v129, 0x4b800000, v128
	v_cndmask_b32_e32 v128, v128, v129, vcc
	v_rsq_f32_e32 v128, v128
	s_nop 0
	v_mul_f32_e32 v129, 0x45800000, v128
	v_cndmask_b32_e32 v156, v128, v129, vcc
	v_lshl_add_u64 v[128:129], v[146:147], 4, s[24:25]
	v_add_u32_e32 v146, s61, v146
	v_ashrrev_i32_e32 v147, 31, v146
	v_mov_b32_e32 v128, v214
	v_mov_b32_e32 v129, v215
	v_mov_b32_e32 v130, v216
	v_mov_b32_e32 v131, v217
	v_mov_b32_e32 v158, v129
	v_mov_b32_e32 v159, v130
	v_mov_b32_e32 v129, v131
	v_pk_add_f32 v[158:159], v[158:159], v[128:129]
	v_lshl_add_u64 v[128:129], v[146:147], 4, s[24:25]
	v_mov_b32_e32 v128, v218
	v_mov_b32_e32 v129, v219
	v_mov_b32_e32 v130, v220
	v_mov_b32_e32 v131, v221
	v_mov_b32_e32 v160, v129
	v_mov_b32_e32 v161, v130
	v_mov_b32_e32 v129, v131
	v_pk_add_f32 v[128:129], v[160:161], v[128:129]
	v_mov_b32_e32 v131, v158
	v_mov_b32_e32 v130, v128
	v_mov_b32_e32 v158, v129
	v_pk_add_f32 v[128:129], v[130:131], v[158:159]
	v_add_u32_e32 v160, s61, v146
	v_pk_fma_f32 v[128:129], v[128:129], s[46:47], v[144:145] op_sel_hi:[1,0,0]
	v_ashrrev_i32_e32 v161, 31, v160
	v_mul_f32_e32 v130, 0x4b800000, v129
	v_cmp_gt_f32_e64 s[4:5], s10, v129
	v_cmp_gt_f32_e32 vcc, s10, v128
	s_nop 0
	v_cndmask_b32_e64 v129, v129, v130, s[4:5]
	v_rsq_f32_e32 v129, v129
	s_nop 0
	v_mul_f32_e32 v130, 0x45800000, v129
	v_cndmask_b32_e64 v157, v129, v130, s[4:5]
	v_mul_f32_e32 v129, 0x4b800000, v128
	v_cndmask_b32_e32 v128, v128, v129, vcc
	v_rsq_f32_e32 v128, v128
	v_mul_f32_e32 v120, v120, v157
	v_mul_f32_e32 v112, v112, v157
	v_mul_f32_e32 v104, v104, v157
	v_mul_f32_e32 v129, 0x45800000, v128
	v_cndmask_b32_e32 v158, v128, v129, vcc
	v_lshl_add_u64 v[128:129], v[160:161], 4, s[24:25]
	v_mul_f32_e32 v121, v121, v158
	v_mul_f32_e32 v113, v113, v158
	v_mul_f32_e32 v105, v105, v158
	v_mul_f32_e32 v96, v96, v157
	v_mul_f32_e32 v97, v97, v158
	v_mul_f32_e32 v88, v88, v157
	v_mul_f32_e32 v89, v89, v158
	v_mul_f32_e32 v80, v80, v157
	v_mul_f32_e32 v81, v81, v158
	v_mul_f32_e32 v72, v72, v157
	v_mul_f32_e32 v73, v73, v158
	v_mul_f32_e32 v64, v64, v157
	v_mul_f32_e32 v65, v65, v158
	v_mov_b32_e32 v128, v222
	v_mov_b32_e32 v129, v223
	v_mov_b32_e32 v130, v224
	v_mov_b32_e32 v131, v225
	v_mov_b32_e32 v146, v129
	v_mov_b32_e32 v147, v130
	v_mov_b32_e32 v129, v131
	v_pk_add_f32 v[146:147], v[146:147], v[128:129]
	v_add_u32_e32 v128, s61, v160
	v_ashrrev_i32_e32 v129, 31, v128
	v_lshl_add_u64 v[128:129], v[128:129], 4, s[24:25]
	v_cvt_pk_bf16_f32 v124, v124, v125
	v_mul_f32_e32 v125, v126, v155
	v_mul_f32_e32 v126, v127, v156
	v_cvt_pk_bf16_f32 v125, v125, v126
	v_cvt_pk_bf16_f32 v126, v120, v121
	v_mov_b32_e32 v128, v226
	v_mov_b32_e32 v129, v227
	v_mov_b32_e32 v130, v228
	v_mov_b32_e32 v131, v229
	s_or_b32 s98, s33, 0x80
	v_or_b32_e32 v166, s98, v151
	v_mul_lo_u32 v166, v166, s61
	v_add_u32_e32 v166, s8, v166
	v_mov_b32_e32 v164, v166
	v_ashrrev_i32_e32 v165, 31, v164
	v_lshl_add_u64 v[162:163], v[164:165], 4, s[24:25]
	global_load_dwordx4 v[184:187], v[162:163], off
	v_add_u32_e32 v164, s61, v164
	v_ashrrev_i32_e32 v165, 31, v164
	v_lshl_add_u64 v[162:163], v[164:165], 4, s[24:25]
	global_load_dwordx4 v[188:191], v[162:163], off
	v_add_u32_e32 v164, s61, v164
	v_ashrrev_i32_e32 v165, 31, v164
	v_lshl_add_u64 v[162:163], v[164:165], 4, s[24:25]
	global_load_dwordx4 v[192:195], v[162:163], off
	v_add_u32_e32 v164, s61, v164
	v_ashrrev_i32_e32 v165, 31, v164
	v_lshl_add_u64 v[162:163], v[164:165], 4, s[24:25]
	global_load_dwordx4 v[196:199], v[162:163], off
	v_add_u32_e32 v164, s61, v164
	v_ashrrev_i32_e32 v165, 31, v164
	v_lshl_add_u64 v[162:163], v[164:165], 4, s[24:25]
	global_load_dwordx4 v[214:217], v[162:163], off
	v_add_u32_e32 v164, s61, v164
	v_ashrrev_i32_e32 v165, 31, v164
	v_lshl_add_u64 v[162:163], v[164:165], 4, s[24:25]
	global_load_dwordx4 v[218:221], v[162:163], off
	v_add_u32_e32 v164, s61, v164
	v_ashrrev_i32_e32 v165, 31, v164
	v_lshl_add_u64 v[162:163], v[164:165], 4, s[24:25]
	global_load_dwordx4 v[222:225], v[162:163], off
	v_add_u32_e32 v164, s61, v164
	v_ashrrev_i32_e32 v165, 31, v164
	v_lshl_add_u64 v[162:163], v[164:165], 4, s[24:25]
	global_load_dwordx4 v[226:229], v[162:163], off
	v_mov_b32_e32 v160, v129
	v_mov_b32_e32 v161, v130
	v_mov_b32_e32 v129, v131
	v_pk_add_f32 v[128:129], v[160:161], v[128:129]
	v_mov_b32_e32 v131, v146
	v_mov_b32_e32 v130, v128
	v_mov_b32_e32 v146, v129
	v_pk_add_f32 v[128:129], v[130:131], v[146:147]
	s_nop 0
	v_pk_fma_f32 v[128:129], v[128:129], s[46:47], v[144:145] op_sel_hi:[1,0,0]
	s_nop 0
	v_mul_f32_e32 v130, 0x4b800000, v129
	v_cmp_gt_f32_e64 s[4:5], s10, v129
	v_cmp_gt_f32_e32 vcc, s10, v128
	s_nop 0
	v_cndmask_b32_e64 v129, v129, v130, s[4:5]
	v_rsq_f32_e32 v129, v129
	s_nop 0
	v_mul_f32_e32 v130, 0x45800000, v129
	v_cndmask_b32_e64 v130, v129, v130, s[4:5]
	v_mul_f32_e32 v129, 0x4b800000, v128
	v_cndmask_b32_e32 v128, v128, v129, vcc
	v_rsq_f32_e32 v128, v128
	s_or_b32 s4, s33, s9
	s_ashr_i32 s4, s4, 5
	s_ashr_i32 s5, s4, 31
	v_mul_f32_e32 v129, 0x45800000, v128
	s_lshl_b64 s[4:5], s[4:5], 14
	v_cndmask_b32_e32 v131, v128, v129, vcc
	v_mul_f32_e32 v120, v122, v130
	s_add_u32 s4, s83, s4
	v_mul_f32_e32 v121, v123, v131
	v_cvt_pk_bf16_f32 v127, v120, v121
	s_addc_u32 s5, s84, s5
	s_lshl_b32 s36, s36, 3
	v_lshlrev_b32_e32 v120, 5, v152
	s_and_b32 s36, s36, 0xfffff800
	v_and_b32_e32 v120, 0x1e0, v120
	v_or_b32_e32 v122, s36, v120
	v_ashrrev_i32_e32 v123, 31, v122
	v_lshlrev_b64 v[120:121], 1, v[122:123]
	v_lshl_add_u64 v[128:129], s[4:5], 0, v[120:121]
	v_lshl_add_u64 v[128:129], v[128:129], 0, v[176:177]
	global_store_dwordx4 v[128:129], v[124:127], off
	v_cvt_pk_bf16_f32 v116, v116, v117
	v_mul_f32_e32 v117, v118, v155
	v_mul_f32_e32 v118, v119, v156
	v_cvt_pk_bf16_f32 v117, v117, v118
	v_cvt_pk_bf16_f32 v118, v112, v113
	v_mul_f32_e32 v112, v114, v130
	v_mul_f32_e32 v113, v115, v131
	v_cvt_pk_bf16_f32 v119, v112, v113
	global_store_dwordx4 v[128:129], v[116:119], off offset:1024
	v_cvt_pk_bf16_f32 v108, v108, v109
	v_mul_f32_e32 v109, v110, v155
	v_mul_f32_e32 v110, v111, v156
	v_cvt_pk_bf16_f32 v109, v109, v110
	v_cvt_pk_bf16_f32 v110, v104, v105
	v_mul_f32_e32 v104, v106, v130
	v_mul_f32_e32 v105, v107, v131
	v_cvt_pk_bf16_f32 v111, v104, v105
	global_store_dwordx4 v[128:129], v[108:111], off offset:2048
	v_cvt_pk_bf16_f32 v100, v100, v101
	v_mul_f32_e32 v101, v102, v155
	v_mul_f32_e32 v102, v103, v156
	v_cvt_pk_bf16_f32 v101, v101, v102
	v_cvt_pk_bf16_f32 v102, v96, v97
	v_mul_f32_e32 v96, v98, v130
	v_mul_f32_e32 v97, v99, v131
	v_cvt_pk_bf16_f32 v103, v96, v97
	global_store_dwordx4 v[128:129], v[100:103], off offset:3072
	v_cvt_pk_bf16_f32 v92, v92, v93
	v_mul_f32_e32 v93, v94, v155
	v_mul_f32_e32 v94, v95, v156
	v_cvt_pk_bf16_f32 v93, v93, v94
	v_cvt_pk_bf16_f32 v94, v88, v89
	v_mul_f32_e32 v88, v90, v130
	v_mul_f32_e32 v89, v91, v131
	v_cvt_pk_bf16_f32 v95, v88, v89
	v_add_u32_e32 v88, 0x1000, v122
	v_ashrrev_i32_e32 v89, 31, v88
	v_lshlrev_b64 v[88:89], 1, v[88:89]
	v_lshl_add_u64 v[90:91], s[4:5], 0, v[88:89]
	v_lshl_add_u64 v[90:91], v[90:91], 0, v[176:177]
	global_store_dwordx4 v[90:91], v[92:95], off
	v_cvt_pk_bf16_f32 v84, v84, v85
	v_mul_f32_e32 v85, v86, v155
	v_mul_f32_e32 v86, v87, v156
	v_cvt_pk_bf16_f32 v85, v85, v86
	v_cvt_pk_bf16_f32 v86, v80, v81
	v_mul_f32_e32 v80, v82, v130
	v_mul_f32_e32 v81, v83, v131
	v_cvt_pk_bf16_f32 v87, v80, v81
	v_add_u32_e32 v80, 0x1200, v122
	v_ashrrev_i32_e32 v81, 31, v80
	v_lshlrev_b64 v[80:81], 1, v[80:81]
	v_lshl_add_u64 v[82:83], s[4:5], 0, v[80:81]
	v_lshl_add_u64 v[82:83], v[82:83], 0, v[176:177]
	global_store_dwordx4 v[82:83], v[84:87], off
	v_cvt_pk_bf16_f32 v76, v76, v77
	v_mul_f32_e32 v77, v78, v155
	v_mul_f32_e32 v78, v79, v156
	v_cvt_pk_bf16_f32 v77, v77, v78
	v_cvt_pk_bf16_f32 v78, v72, v73
	v_mul_f32_e32 v72, v74, v130
	v_mul_f32_e32 v73, v75, v131
	v_cvt_pk_bf16_f32 v79, v72, v73
	v_add_u32_e32 v72, 0x1400, v122
	v_ashrrev_i32_e32 v73, 31, v72
	v_lshlrev_b64 v[72:73], 1, v[72:73]
	v_lshl_add_u64 v[74:75], s[4:5], 0, v[72:73]
	v_lshl_add_u64 v[74:75], v[74:75], 0, v[176:177]
	global_store_dwordx4 v[74:75], v[76:79], off
	v_cvt_pk_bf16_f32 v74, v68, v69
	v_mul_f32_e32 v68, v70, v155
	v_mul_f32_e32 v69, v71, v156
	v_cvt_pk_bf16_f32 v75, v68, v69
	v_cvt_pk_bf16_f32 v76, v64, v65
	v_mul_f32_e32 v64, v66, v130
	v_mul_f32_e32 v65, v67, v131
	v_cvt_pk_bf16_f32 v77, v64, v65
	v_add_u32_e32 v64, 0x1600, v122
	v_ashrrev_i32_e32 v65, 31, v64
	v_lshlrev_b64 v[68:69], 1, v[64:65]
	v_lshl_add_u64 v[64:65], s[4:5], 0, v[68:69]
	v_lshl_add_u64 v[64:65], v[64:65], 0, v[176:177]
	s_bitset1_b32 s33, 7
	global_store_dwordx4 v[64:65], v[74:77], off
	v_or_b32_e32 v64, s33, v151
	v_mul_lo_u32 v64, v64, s61
	v_add_u32_e32 v70, s8, v64
	v_ashrrev_i32_e32 v71, 31, v70
	v_lshl_add_u64 v[64:65], v[70:71], 4, s[24:25]
	v_add_u32_e32 v70, s61, v70
	v_ashrrev_i32_e32 v71, 31, v70
	s_waitcnt vmcnt(0)
	v_mov_b32_e32 v64, v184
	v_mov_b32_e32 v65, v185
	v_mov_b32_e32 v66, v186
	v_mov_b32_e32 v67, v187
	v_mov_b32_e32 v74, v65
	v_mov_b32_e32 v75, v66
	v_mov_b32_e32 v65, v67
	v_pk_add_f32 v[74:75], v[74:75], v[64:65]
	v_lshl_add_u64 v[64:65], v[70:71], 4, s[24:25]
	v_add_u32_e32 v70, s61, v70
	v_ashrrev_i32_e32 v71, 31, v70
	v_mov_b32_e32 v64, v188
	v_mov_b32_e32 v65, v189
	v_mov_b32_e32 v66, v190
	v_mov_b32_e32 v67, v191
	v_mov_b32_e32 v76, v65
	v_mov_b32_e32 v77, v66
	v_mov_b32_e32 v65, v67
	v_pk_add_f32 v[64:65], v[76:77], v[64:65]
	v_mov_b32_e32 v67, v74
	v_mov_b32_e32 v66, v64
	v_mov_b32_e32 v74, v65
	v_pk_add_f32 v[64:65], v[66:67], v[74:75]
	s_nop 0
	v_pk_fma_f32 v[64:65], v[64:65], s[46:47], v[144:145] op_sel_hi:[1,0,0]
	s_nop 0
	v_mul_f32_e32 v66, 0x4b800000, v65
	v_cmp_gt_f32_e64 s[4:5], s10, v65
	v_cmp_gt_f32_e32 vcc, s10, v64
	s_nop 0
	v_cndmask_b32_e64 v65, v65, v66, s[4:5]
	v_rsq_f32_e32 v65, v65
	s_nop 0
	v_mul_f32_e32 v66, 0x45800000, v65
	v_cndmask_b32_e64 v74, v65, v66, s[4:5]
	v_mul_f32_e32 v65, 0x4b800000, v64
	v_cndmask_b32_e32 v64, v64, v65, vcc
	v_rsq_f32_e32 v64, v64
	v_mul_f32_e32 v60, v60, v74
	v_mul_f32_e32 v52, v52, v74
	v_mul_f32_e32 v44, v44, v74
	v_mul_f32_e32 v65, 0x45800000, v64
	v_cndmask_b32_e32 v75, v64, v65, vcc
	v_lshl_add_u64 v[64:65], v[70:71], 4, s[24:25]
	v_add_u32_e32 v70, s61, v70
	v_ashrrev_i32_e32 v71, 31, v70
	v_mul_f32_e32 v61, v61, v75
	v_mul_f32_e32 v53, v53, v75
	v_mul_f32_e32 v45, v45, v75
	v_mul_f32_e32 v36, v36, v74
	v_mul_f32_e32 v37, v37, v75
	v_mul_f32_e32 v28, v28, v74
	v_mul_f32_e32 v29, v29, v75
	v_mul_f32_e32 v20, v20, v74
	v_mul_f32_e32 v21, v21, v75
	v_mul_f32_e32 v12, v12, v74
	v_mul_f32_e32 v13, v13, v75
	v_mul_f32_e32 v4, v4, v74
	v_mul_f32_e32 v5, v5, v75
	v_mov_b32_e32 v64, v192
	v_mov_b32_e32 v65, v193
	v_mov_b32_e32 v66, v194
	v_mov_b32_e32 v67, v195
	v_mov_b32_e32 v76, v65
	v_mov_b32_e32 v77, v66
	v_mov_b32_e32 v65, v67
	v_pk_add_f32 v[76:77], v[76:77], v[64:65]
	v_lshl_add_u64 v[64:65], v[70:71], 4, s[24:25]
	v_add_u32_e32 v70, s61, v70
	v_ashrrev_i32_e32 v71, 31, v70
	v_mov_b32_e32 v64, v196
	v_mov_b32_e32 v65, v197
	v_mov_b32_e32 v66, v198
	v_mov_b32_e32 v67, v199
	v_mov_b32_e32 v78, v65
	v_mov_b32_e32 v79, v66
	v_mov_b32_e32 v65, v67
	v_pk_add_f32 v[64:65], v[78:79], v[64:65]
	v_mov_b32_e32 v67, v76
	v_mov_b32_e32 v66, v64
	v_mov_b32_e32 v76, v65
	v_pk_add_f32 v[64:65], v[66:67], v[76:77]
	s_nop 0
	v_pk_fma_f32 v[64:65], v[64:65], s[46:47], v[144:145] op_sel_hi:[1,0,0]
	s_nop 0
	v_mul_f32_e32 v66, 0x4b800000, v65
	v_cmp_gt_f32_e64 s[4:5], s10, v65
	v_cmp_gt_f32_e32 vcc, s10, v64
	s_nop 0
	v_cndmask_b32_e64 v65, v65, v66, s[4:5]
	v_rsq_f32_e32 v65, v65
	s_nop 0
	v_mul_f32_e32 v66, 0x45800000, v65
	v_cndmask_b32_e64 v76, v65, v66, s[4:5]
	v_mul_f32_e32 v65, 0x4b800000, v64
	v_cndmask_b32_e32 v64, v64, v65, vcc
	v_rsq_f32_e32 v64, v64
	s_nop 0
	v_mul_f32_e32 v65, 0x45800000, v64
	v_cndmask_b32_e32 v77, v64, v65, vcc
	v_lshl_add_u64 v[64:65], v[70:71], 4, s[24:25]
	v_add_u32_e32 v70, s61, v70
	v_ashrrev_i32_e32 v71, 31, v70
	v_mov_b32_e32 v64, v214
	v_mov_b32_e32 v65, v215
	v_mov_b32_e32 v66, v216
	v_mov_b32_e32 v67, v217
	v_mov_b32_e32 v78, v65
	v_mov_b32_e32 v79, v66
	v_mov_b32_e32 v65, v67
	v_pk_add_f32 v[78:79], v[78:79], v[64:65]
	v_lshl_add_u64 v[64:65], v[70:71], 4, s[24:25]
	v_mov_b32_e32 v64, v218
	v_mov_b32_e32 v65, v219
	v_mov_b32_e32 v66, v220
	v_mov_b32_e32 v67, v221
	v_mov_b32_e32 v82, v65
	v_mov_b32_e32 v83, v66
	v_mov_b32_e32 v65, v67
	v_pk_add_f32 v[64:65], v[82:83], v[64:65]
	v_mov_b32_e32 v67, v78
	v_mov_b32_e32 v66, v64
	v_mov_b32_e32 v78, v65
	v_pk_add_f32 v[64:65], v[66:67], v[78:79]
	v_add_u32_e32 v82, s61, v70
	v_pk_fma_f32 v[64:65], v[64:65], s[46:47], v[144:145] op_sel_hi:[1,0,0]
	v_ashrrev_i32_e32 v83, 31, v82
	v_mul_f32_e32 v66, 0x4b800000, v65
	v_cmp_gt_f32_e64 s[4:5], s10, v65
	v_cmp_gt_f32_e32 vcc, s10, v64
	s_nop 0
	v_cndmask_b32_e64 v65, v65, v66, s[4:5]
	v_rsq_f32_e32 v65, v65
	s_nop 0
	v_mul_f32_e32 v66, 0x45800000, v65
	v_cndmask_b32_e64 v78, v65, v66, s[4:5]
	v_mul_f32_e32 v65, 0x4b800000, v64
	v_cndmask_b32_e32 v64, v64, v65, vcc
	v_rsq_f32_e32 v64, v64
	v_mul_f32_e32 v56, v56, v78
	v_mul_f32_e32 v48, v48, v78
	v_mul_f32_e32 v40, v40, v78
	v_mul_f32_e32 v65, 0x45800000, v64
	v_cndmask_b32_e32 v79, v64, v65, vcc
	v_lshl_add_u64 v[64:65], v[82:83], 4, s[24:25]
	v_mul_f32_e32 v57, v57, v79
	v_mul_f32_e32 v49, v49, v79
	v_mul_f32_e32 v41, v41, v79
	v_mul_f32_e32 v32, v32, v78
	v_mul_f32_e32 v33, v33, v79
	v_mul_f32_e32 v24, v24, v78
	v_mul_f32_e32 v25, v25, v79
	v_mul_f32_e32 v16, v16, v78
	v_mul_f32_e32 v17, v17, v79
	v_mul_f32_e32 v8, v8, v78
	v_mul_f32_e32 v9, v9, v79
	v_mul_f32_e32 v0, v0, v78
	v_mul_f32_e32 v1, v1, v79
	v_mov_b32_e32 v64, v222
	v_mov_b32_e32 v65, v223
	v_mov_b32_e32 v66, v224
	v_mov_b32_e32 v67, v225
	v_mov_b32_e32 v70, v65
	v_mov_b32_e32 v71, v66
	v_mov_b32_e32 v65, v67
	v_pk_add_f32 v[70:71], v[70:71], v[64:65]
	v_add_u32_e32 v64, s61, v82
	v_ashrrev_i32_e32 v65, 31, v64
	v_lshl_add_u64 v[64:65], v[64:65], 4, s[24:25]
	v_cvt_pk_bf16_f32 v60, v60, v61
	v_mul_f32_e32 v61, v62, v76
	v_mul_f32_e32 v62, v63, v77
	v_cvt_pk_bf16_f32 v61, v61, v62
	v_cvt_pk_bf16_f32 v62, v56, v57
	v_mov_b32_e32 v64, v226
	v_mov_b32_e32 v65, v227
	v_mov_b32_e32 v66, v228
	v_mov_b32_e32 v67, v229
	v_mov_b32_e32 v82, v65
	v_mov_b32_e32 v83, v66
	v_mov_b32_e32 v65, v67
	v_pk_add_f32 v[64:65], v[82:83], v[64:65]
	v_mov_b32_e32 v67, v70
	v_mov_b32_e32 v66, v64
	v_mov_b32_e32 v70, v65
	v_pk_add_f32 v[64:65], v[66:67], v[70:71]
	s_nop 0
	v_pk_fma_f32 v[64:65], v[64:65], s[46:47], v[144:145] op_sel_hi:[1,0,0]
	s_nop 0
	v_mul_f32_e32 v66, 0x4b800000, v65
	v_cmp_gt_f32_e64 s[4:5], s10, v65
	v_cmp_gt_f32_e32 vcc, s10, v64
	s_nop 0
	v_cndmask_b32_e64 v65, v65, v66, s[4:5]
	v_rsq_f32_e32 v65, v65
	s_nop 0
	v_mul_f32_e32 v66, 0x45800000, v65
	v_cndmask_b32_e64 v65, v65, v66, s[4:5]
	v_mul_f32_e32 v66, 0x4b800000, v64
	v_cndmask_b32_e32 v64, v64, v66, vcc
	v_rsq_f32_e32 v64, v64
	s_or_b32 s4, s33, s9
	s_ashr_i32 s4, s4, 5
	s_ashr_i32 s5, s4, 31
	v_mul_f32_e32 v66, 0x45800000, v64
	s_lshl_b64 s[4:5], s[4:5], 14
	v_cndmask_b32_e32 v64, v64, v66, vcc
	s_add_u32 s4, s83, s4
	v_mul_f32_e32 v56, v58, v65
	v_mul_f32_e32 v57, v59, v64
	s_addc_u32 s5, s84, s5
	v_cvt_pk_bf16_f32 v63, v56, v57
	v_lshl_add_u64 v[56:57], s[4:5], 0, v[120:121]
	v_lshl_add_u64 v[56:57], v[56:57], 0, v[176:177]
	global_store_dwordx4 v[56:57], v[60:63], off
	v_cvt_pk_bf16_f32 v52, v52, v53
	v_mul_f32_e32 v53, v54, v76
	v_mul_f32_e32 v54, v55, v77
	v_cvt_pk_bf16_f32 v53, v53, v54
	v_cvt_pk_bf16_f32 v54, v48, v49
	v_mul_f32_e32 v48, v50, v65
	v_mul_f32_e32 v49, v51, v64
	v_cvt_pk_bf16_f32 v55, v48, v49
	global_store_dwordx4 v[56:57], v[52:55], off offset:1024
	v_cvt_pk_bf16_f32 v44, v44, v45
	v_mul_f32_e32 v45, v46, v76
	v_mul_f32_e32 v46, v47, v77
	v_cvt_pk_bf16_f32 v45, v45, v46
	v_cvt_pk_bf16_f32 v46, v40, v41
	v_mul_f32_e32 v40, v42, v65
	v_mul_f32_e32 v41, v43, v64
	v_cvt_pk_bf16_f32 v47, v40, v41
	global_store_dwordx4 v[56:57], v[44:47], off offset:2048
	v_cvt_pk_bf16_f32 v36, v36, v37
	v_mul_f32_e32 v37, v38, v76
	v_mul_f32_e32 v38, v39, v77
	v_cvt_pk_bf16_f32 v37, v37, v38
	v_cvt_pk_bf16_f32 v38, v32, v33
	v_mul_f32_e32 v32, v34, v65
	v_mul_f32_e32 v33, v35, v64
	v_cvt_pk_bf16_f32 v39, v32, v33
	global_store_dwordx4 v[56:57], v[36:39], off offset:3072
	v_cvt_pk_bf16_f32 v28, v28, v29
	v_mul_f32_e32 v29, v30, v76
	v_mul_f32_e32 v30, v31, v77
	v_cvt_pk_bf16_f32 v29, v29, v30
	v_cvt_pk_bf16_f32 v30, v24, v25
	v_mul_f32_e32 v24, v26, v65
	v_mul_f32_e32 v25, v27, v64
	v_cvt_pk_bf16_f32 v31, v24, v25
	v_lshl_add_u64 v[24:25], s[4:5], 0, v[88:89]
	v_lshl_add_u64 v[24:25], v[24:25], 0, v[176:177]
	global_store_dwordx4 v[24:25], v[28:31], off
	v_cvt_pk_bf16_f32 v20, v20, v21
	v_mul_f32_e32 v21, v22, v76
	v_mul_f32_e32 v22, v23, v77
	v_cvt_pk_bf16_f32 v21, v21, v22
	v_cvt_pk_bf16_f32 v22, v16, v17
	v_mul_f32_e32 v16, v18, v65
	v_mul_f32_e32 v17, v19, v64
	v_cvt_pk_bf16_f32 v23, v16, v17
	v_lshl_add_u64 v[16:17], s[4:5], 0, v[80:81]
	v_lshl_add_u64 v[16:17], v[16:17], 0, v[176:177]
	global_store_dwordx4 v[16:17], v[20:23], off
	v_cvt_pk_bf16_f32 v12, v12, v13
	v_mul_f32_e32 v13, v14, v76
	v_mul_f32_e32 v14, v15, v77
	v_cvt_pk_bf16_f32 v13, v13, v14
	v_cvt_pk_bf16_f32 v14, v8, v9
	v_mul_f32_e32 v8, v10, v65
	v_mul_f32_e32 v9, v11, v64
	v_cvt_pk_bf16_f32 v15, v8, v9
	v_lshl_add_u64 v[8:9], s[4:5], 0, v[72:73]
	v_lshl_add_u64 v[8:9], v[8:9], 0, v[176:177]
	global_store_dwordx4 v[8:9], v[12:15], off
	v_cvt_pk_bf16_f32 v4, v4, v5
	v_mul_f32_e32 v5, v6, v76
	v_mul_f32_e32 v6, v7, v77
	v_cvt_pk_bf16_f32 v5, v5, v6
	v_cvt_pk_bf16_f32 v6, v0, v1
	v_mul_f32_e32 v0, v2, v65
	v_mul_f32_e32 v1, v3, v64
	v_cvt_pk_bf16_f32 v7, v0, v1
	v_lshl_add_u64 v[0:1], s[4:5], 0, v[68:69]
	v_lshl_add_u64 v[0:1], v[0:1], 0, v[176:177]
	global_store_dwordx4 v[0:1], v[4:7], off
	s_mov_b64 s[4:5], -1
	s_andn2_b64 vcc, exec, s[38:39]
	s_cbranch_vccnz .LBB0_507
	s_andn2_b64 vcc, exec, s[42:43]
	s_cbranch_vccnz .LBB0_506
	s_barrier
	s_branch .LBB0_506
